# v33 + top-k select: merged SEL stores (fewer store instructions in radix-select scans)
# speedup vs baseline: 1.0033x; 1.0033x over previous
; DI void radix_select(unsigned* sc, int* hist, int* misc, int n, unsigned long long* sel, int tid, int lane, int w) {
;     ...
;     for (int i0 = beg; i0 < beg + seg; i0 += 256) {
;       unsigned u[4]; bool in[4];
; #pragma unroll
;       for (int c = 0; c < 4; ++c) {
;         const int ib = i0 + c * 64, i = ib + lane;
;         in[c] = (ib < beg + seg) && (i < n);
;         u[c] = in[c] ? sc[i] : 0u;
;       }
; #pragma unroll
;       for (int c = 0; c < 4; ++c) {
;         const int ib = i0 + c * 64;
;         const unsigned long long sm = __ballot(in[c] && u[c] >= T);
;         if (lane == 0 && ib < beg + seg && ib < n) sel[ib >> 6] = sm;
;       }
.LBB0_1442:
	v_add_u32_e32 v15, v179, v6
	v_cmp_lt_u32_e64 s[22:23], v6, v30
	v_cmp_lt_u32_e32 vcc, v15, v206
	s_and_b64 s[88:89], s[22:23], vcc
	v_mov_b32_e32 v11, 0
	v_mov_b32_e32 v14, 0
	s_and_saveexec_b64 s[0:1], s[88:89]
	ds_read_b32 v14, v5
	s_or_b64 exec, exec, s[0:1]
	v_add_u32_e32 v10, 64, v6
	v_add_u32_e32 v7, 64, v15
	v_cmp_lt_u32_e64 s[24:25], v10, v30
	v_cmp_lt_u32_e32 vcc, v7, v206
	s_and_b64 s[92:93], s[24:25], vcc
	s_and_saveexec_b64 s[0:1], s[92:93]
	ds_read_b32 v11, v5 offset:256
	s_or_b64 exec, exec, s[0:1]
	v_add_u32_e32 v9, 0x80, v6
	v_add_u32_e32 v7, 0x80, v15
	v_cmp_lt_u32_e64 s[20:21], v9, v30
	v_cmp_lt_u32_e32 vcc, v7, v206
	s_and_b64 s[42:43], s[20:21], vcc
	v_mov_b32_e32 v8, 0
	v_mov_b32_e32 v13, 0
	s_and_saveexec_b64 s[0:1], s[42:43]
	ds_read_b32 v13, v5 offset:512
	s_or_b64 exec, exec, s[0:1]
	v_add_u32_e32 v7, 0xc0, v6
	v_add_u32_e32 v15, 0xc0, v15
	v_cmp_lt_u32_e32 vcc, v7, v30
	v_cmp_lt_u32_e64 s[26:27], v15, v206
	s_and_b64 s[0:1], vcc, s[26:27]
	s_and_saveexec_b64 s[26:27], s[0:1]
	ds_read_b32 v8, v5 offset:768
	s_or_b64 exec, exec, s[26:27]
	s_waitcnt lgkmcnt(0)
	v_cmp_ge_u32_e64 s[26:27], v14, v12
	v_cmp_ge_u32_e64 s[98:99], v11, v12
	v_cmp_ge_u32_e64 s[100:101], v13, v12
	v_cmp_ge_u32_e64 s[86:87], v8, v12
	s_and_b64 s[26:27], s[88:89], s[26:27]
	s_and_b64 s[98:99], s[92:93], s[98:99]
	s_and_b64 s[100:101], s[42:43], s[100:101]
	s_and_b64 s[86:87], s[0:1], s[86:87]
	v_mov_b32_e32 v14, s26
	v_mov_b32_e32 v15, s27
	v_writelane_b32 v14, s98, 1
	v_writelane_b32 v15, s99, 1
	v_writelane_b32 v14, s100, 2
	v_writelane_b32 v15, s101, 2
	v_writelane_b32 v14, s86, 3
	v_writelane_b32 v15, s87, 3
	v_readfirstlane_b32 s22, v6
	v_and_b32_e32 v10, 63, v203
	v_lshlrev_b32_e32 v11, 6, v10
	s_nop 0
	v_add_u32_e32 v11, s22, v11
	v_cmp_gt_u32_e32 vcc, 4, v10
	v_cmp_lt_u32_e64 s[22:23], v11, v30
	v_cmp_lt_u32_e64 s[24:25], v11, v206
	v_lshlrev_b32_e32 v10, 3, v10
	v_mov_b32_e32 v11, 0
	s_and_b64 s[22:23], s[22:23], vcc
	s_and_b64 s[22:23], s[22:23], s[24:25]
	v_lshl_add_u64 v[10:11], v[2:3], 0, v[10:11]
	s_and_saveexec_b64 s[20:21], s[22:23]
	global_store_dwordx2 v[10:11], v[14:15], off
	s_branch .LBB0_1441

; DI void radix_select(unsigned* sc, int* hist, int* misc, int n, unsigned long long* sel, int tid, int lane, int w) {
;     ...
;     for (int i0 = beg; i0 < beg + seg; i0 += 256) {
;       unsigned u[4]; bool in[4];
; #pragma unroll
;       for (int c = 0; c < 4; ++c) {
;         const int ib = i0 + c * 64, i = ib + lane;
;         in[c] = (ib < beg + seg) && (i < n);
;         u[c] = in[c] ? sc[i] : 0u;
;       }
; #pragma unroll
;       for (int c = 0; c < 4; ++c) {
;         const int ib = i0 + c * 64;
;         const unsigned long long sm = __ballot(in[c] && u[c] >= T);
;         if (lane == 0 && ib < beg + seg && ib < n) sel[ib >> 6] = sm;
;       }
.LBB0_1513:
	v_add_u32_e32 v37, v179, v5
	v_cmp_lt_u32_e64 s[26:27], v5, v30
	v_cmp_lt_u32_e32 vcc, v37, v206
	s_and_b64 s[92:93], s[26:27], vcc
	v_mov_b32_e32 v34, 0
	v_mov_b32_e32 v36, 0
	s_and_saveexec_b64 s[24:25], s[92:93]
	ds_read_b32 v36, v4
	s_or_b64 exec, exec, s[24:25]
	v_add_u32_e32 v15, 64, v5
	v_add_u32_e32 v6, 64, v37
	v_cmp_lt_u32_e64 s[28:29], v15, v30
	v_cmp_lt_u32_e32 vcc, v6, v206
	s_and_b64 s[86:87], s[28:29], vcc
	s_and_saveexec_b64 s[24:25], s[86:87]
	ds_read_b32 v34, v4 offset:256
	s_or_b64 exec, exec, s[24:25]
	v_add_u32_e32 v14, 0x80, v5
	v_add_u32_e32 v6, 0x80, v37
	v_cmp_lt_u32_e64 s[24:25], v14, v30
	v_cmp_lt_u32_e32 vcc, v6, v206
	s_and_b64 s[88:89], s[24:25], vcc
	v_mov_b32_e32 v7, 0
	v_mov_b32_e32 v35, 0
	s_and_saveexec_b64 s[34:35], s[88:89]
	ds_read_b32 v35, v4 offset:512
	s_or_b64 exec, exec, s[34:35]
	v_add_u32_e32 v6, 0xc0, v5
	v_add_u32_e32 v37, 0xc0, v37
	v_cmp_lt_u32_e32 vcc, v6, v30
	v_cmp_lt_u32_e64 s[34:35], v37, v206
	s_and_b64 s[94:95], vcc, s[34:35]
	s_and_saveexec_b64 s[34:35], s[94:95]
	ds_read_b32 v7, v4 offset:768
	s_or_b64 exec, exec, s[34:35]
	s_waitcnt lgkmcnt(0)
	v_cmp_ge_u32_e64 s[34:35], v36, v33
	v_cmp_ge_u32_e64 s[98:99], v34, v33
	v_cmp_ge_u32_e64 s[100:101], v35, v33
	v_cmp_ge_u32_e64 s[30:31], v7, v33
	s_and_b64 s[34:35], s[92:93], s[34:35]
	s_and_b64 s[98:99], s[86:87], s[98:99]
	s_and_b64 s[100:101], s[88:89], s[100:101]
	s_and_b64 s[30:31], s[94:95], s[30:31]
	v_mov_b32_e32 v36, s34
	v_mov_b32_e32 v37, s35
	v_writelane_b32 v36, s98, 1
	v_writelane_b32 v37, s99, 1
	v_writelane_b32 v36, s100, 2
	v_writelane_b32 v37, s101, 2
	v_writelane_b32 v36, s30, 3
	v_writelane_b32 v37, s31, 3
	v_readfirstlane_b32 s24, v5
	v_and_b32_e32 v34, 63, v203
	v_lshlrev_b32_e32 v35, 6, v34
	s_nop 0
	v_add_u32_e32 v35, s24, v35
	v_cmp_gt_u32_e32 vcc, 4, v34
	v_cmp_lt_u32_e64 s[24:25], v35, v30
	v_cmp_lt_u32_e64 s[28:29], v35, v206
	v_lshlrev_b32_e32 v34, 3, v34
	v_mov_b32_e32 v35, 0
	s_and_b64 s[24:25], s[24:25], vcc
	s_and_b64 s[24:25], s[24:25], s[28:29]
	v_lshl_add_u64 v[34:35], v[2:3], 0, v[34:35]
	s_and_saveexec_b64 s[26:27], s[24:25]
	global_store_dwordx2 v[34:35], v[36:37], off
	s_branch .LBB0_1512
